# scan phase: unit index bit-swizzle so the 8 v-slices of one (b,h,dir) share an XCD (L2 reuse of K/Q chunks)
# speedup vs baseline: 1.0242x; 1.0242x over previous
.LBB0_611:
	v_readlane_b32 s46, v254, 20
	s_and_b32 s54, s33, 7
	s_bfe_u32 s55, s33, 0x30003
	s_lshl_b32 s54, s54, 3
	s_andn2_b32 s33, s33, 63
	s_or_b32 s33, s33, s54
	s_or_b32 s33, s33, s55
	s_add_i32 s33, s33, s46
	v_readlane_b32 s54, v254, 16
	s_cmpk_gt_i32 s33, 0xff
	v_readlane_b32 s57, v254, 12
	v_readlane_b32 s58, v254, 13
	v_readlane_b32 s60, v254, 14
	v_readlane_b32 s55, v254, 17
	v_readlane_b32 s59, v254, 18
	s_movk_i32 s56, 0x3fff
	v_readlane_b32 s47, v254, 21
	v_readlane_b32 s61, v254, 15
	s_cbranch_scc1 .LBB0_681

.LBB0_615:
	s_or_b64 exec, exec, s[46:47]
	s_and_b32 s54, s33, 7
	s_bfe_u32 s55, s33, 0x30003
	s_lshl_b32 s54, s54, 3
	s_andn2_b32 s33, s33, 63
	s_or_b32 s33, s33, s54
	s_or_b32 s33, s33, s55
	s_ashr_i32 s58, s33, 6
	s_bfe_u32 s54, s33, 0x20004
	s_bfe_u32 s55, s33, 0x10003
	s_cmp_eq_u32 s55, 0
	s_cselect_b64 s[46:47], -1, 0
	s_lshl_b32 s56, s58, 8
	v_sub_u32_e32 v1, 0x7f, v173
	s_addk_i32 s56, 0x4000
	s_lshl_b32 s50, s55, 7
	v_cndmask_b32_e64 v197, v1, v173, s[46:47]
	v_sub_u32_e32 v1, 0x7f, v174
	s_or_b32 s52, s56, s50
	v_cndmask_b32_e64 v198, v1, v174, s[46:47]
	v_readlane_b32 s50, v254, 2
	v_add_u32_e32 v2, s52, v197
	s_waitcnt vmcnt(8)
	v_add_u32_e32 v4, s52, v198
	v_readlane_b32 s51, v254, 3
	s_lshl_b32 s50, s54, 9
	v_ashrrev_i32_e32 v3, 31, v2
	v_ashrrev_i32_e32 v5, 31, v4
	v_sub_u32_e32 v1, 0x7f, v175
	v_lshl_add_u64 v[148:149], v[136:137], 0, s[50:51]
	v_lshlrev_b64 v[2:3], 11, v[2:3]
	v_lshlrev_b64 v[4:5], 11, v[4:5]
	v_cndmask_b32_e64 v199, v1, v175, s[46:47]
	v_sub_u32_e32 v1, 0x7f, v176
	v_lshl_add_u64 v[2:3], v[148:149], 0, v[2:3]
	s_waitcnt vmcnt(7)
	v_lshl_add_u64 v[8:9], v[148:149], 0, v[4:5]
	v_cndmask_b32_e64 v200, v1, v176, s[46:47]
	global_load_dwordx4 v[4:7], v[2:3], off
	s_nop 0
	global_load_dwordx4 v[8:11], v[8:9], off
	v_add_u32_e32 v2, s52, v199
	s_waitcnt vmcnt(8)
	v_add_u32_e32 v12, s52, v200
	v_ashrrev_i32_e32 v3, 31, v2
	v_ashrrev_i32_e32 v13, 31, v12
	v_sub_u32_e32 v1, 0x7f, v177
	v_lshlrev_b64 v[2:3], 11, v[2:3]
	v_lshlrev_b64 v[12:13], 11, v[12:13]
	v_cndmask_b32_e64 v201, v1, v177, s[46:47]
	v_sub_u32_e32 v1, 0x7f, v178
	v_lshl_add_u64 v[2:3], v[148:149], 0, v[2:3]
	s_waitcnt vmcnt(7)
	v_lshl_add_u64 v[16:17], v[148:149], 0, v[12:13]
	v_cndmask_b32_e64 v202, v1, v178, s[46:47]
	global_load_dwordx4 v[12:15], v[2:3], off
	s_nop 0
	global_load_dwordx4 v[16:19], v[16:17], off
	v_add_u32_e32 v2, s52, v201
	s_waitcnt vmcnt(8)
	v_add_u32_e32 v20, s52, v202
	v_ashrrev_i32_e32 v3, 31, v2
	v_ashrrev_i32_e32 v21, 31, v20
	v_lshlrev_b64 v[2:3], 11, v[2:3]
	v_lshlrev_b64 v[20:21], 11, v[20:21]
	v_sub_u32_e32 v1, 0x7f, v179
	v_lshl_add_u64 v[2:3], v[148:149], 0, v[2:3]
	s_waitcnt vmcnt(7)
	v_lshl_add_u64 v[24:25], v[148:149], 0, v[20:21]
	v_cndmask_b32_e64 v203, v1, v179, s[46:47]
	v_cndmask_b32_e64 v204, v181, v180, s[46:47]
	global_load_dwordx4 v[20:23], v[2:3], off
	s_nop 0
	global_load_dwordx4 v[24:27], v[24:25], off
	v_add_u32_e32 v2, s52, v203
	s_waitcnt vmcnt(8)
	v_add_u32_e32 v28, s52, v204
	v_ashrrev_i32_e32 v3, 31, v2
	v_ashrrev_i32_e32 v29, 31, v28
	v_lshlrev_b64 v[2:3], 11, v[2:3]
	v_lshlrev_b64 v[28:29], 11, v[28:29]
	v_lshl_add_u64 v[2:3], v[148:149], 0, v[2:3]
	s_waitcnt vmcnt(7)
	v_lshl_add_u64 v[32:33], v[148:149], 0, v[28:29]
	v_cndmask_b32_e64 v205, v161, v160, s[46:47]
	global_load_dwordx4 v[28:31], v[2:3], off
	s_nop 0
	global_load_dwordx4 v[32:35], v[32:33], off
	v_or_b32_e32 v2, s52, v205
	v_ashrrev_i32_e32 v3, 31, v2
	v_readlane_b32 s60, v254, 38
	v_lshlrev_b64 v[2:3], 11, v[2:3]
	v_readlane_b32 s61, v254, 39
	v_mov_b32_e32 v1, v0
	v_mov_b32_e32 v153, 0
	v_lshl_add_u64 v[2:3], s[60:61], 0, v[2:3]
	v_lshl_add_u64 v[2:3], v[2:3], 0, s[50:51]
	s_lshl_b32 s50, s33, 5
	s_and_b32 s50, s50, 0xe0
	s_lshl_b32 s50, s50, 1
	v_writelane_b32 v254, s50, 2
	s_waitcnt vmcnt(8)
	v_mov_b32_e32 v209, 0
	v_mov_b32_e32 v208, 0
	v_lshl_add_u64 v[2:3], v[2:3], 0, s[50:51]
	v_lshl_add_u64 v[2:3], v[138:139], 1, v[2:3]
	global_load_dwordx4 v[36:39], v[2:3], off
	v_sub_u32_e32 v2, 0x7f, v162
	v_cndmask_b32_e64 v206, v2, v162, s[46:47]
	v_sub_u32_e32 v2, 0x7f, v163
	v_writelane_b32 v254, s51, 3
	v_cndmask_b32_e64 v207, v2, v163, s[46:47]
	v_mov_b64_e32 v[150:151], v[0:1]
	s_and_saveexec_b64 s[50:51], s[10:11]
	s_cbranch_execz .LBB0_617
	v_or_b32_e32 v2, s52, v206
	v_ashrrev_i32_e32 v3, 31, v2
	v_readlane_b32 vcc_lo, v254, 40
	v_readlane_b32 s62, v254, 2
	v_or_b32_e32 v40, s52, v207
	v_lshlrev_b64 v[2:3], 6, v[2:3]
	v_readlane_b32 vcc_hi, v254, 41
	v_readlane_b32 s63, v254, 3
	v_ashrrev_i32_e32 v41, 31, v40
	v_lshl_add_u64 v[2:3], vcc, 0, v[2:3]
	s_lshl_b32 s60, s55, 5
	s_mov_b32 s61, s63
	v_lshlrev_b64 v[40:41], 6, v[40:41]
	v_lshl_add_u64 v[2:3], v[2:3], 0, s[60:61]
	s_lshl_b32 s62, s54, 2
	v_lshl_add_u64 v[40:41], vcc, 0, v[40:41]
	v_lshl_add_u64 v[2:3], v[2:3], 0, s[62:63]
	v_lshl_add_u64 v[40:41], v[40:41], 0, s[60:61]
	v_lshl_add_u64 v[40:41], v[40:41], 0, s[62:63]
	global_load_dword v150, v[2:3], off
	global_load_dword v208, v[2:3], off offset:16
	global_load_dword v151, v[40:41], off
	global_load_dword v209, v[40:41], off offset:16
